# P6 epilogue part 1: second x1 load batch issued together with the first
# speedup vs baseline: 1.0248x; 1.0054x over previous
;     __device__ __forceinline__ void operator()(f32x4 (&acc)[2][2][4][2], const Unit& u, int wr, int wc, int fr, int fq) const {
;     ...
;         for (int ai = 0; ai < 2; ++ai) {
;             u32x4 xv[4][2];
; #pragma unroll
;             for (int m = 0; m < 4; ++m)
; #pragma unroll
;                 for (int bj = 0; bj < 2; ++bj) { const size_t off = (size_t)(row0 + ai * HALF + m * 16) * DM + col0 + bj * HALF; xv[m][bj] = *(const u32x4*)(xb + off); }
; #pragma unroll
;             for (int m = 0; m < 4; ++m) { const size_t r = (size_t)(row0 + ai * HALF + m * 16); float ss = 0.f;
; #pragma unroll
;                 for (int bj = 0; bj < 2; ++bj) { const u32x4 xw = xv[m][bj];
;                     const f32x4 x0 = {bf_lo(xw.x), bf_hi(xw.x), bf_lo(xw.y), bf_hi(xw.y)}, x1 = {bf_lo(xw.z), bf_hi(xw.z), bf_lo(xw.w), bf_hi(xw.w)};
;                     const f32x4 v0 = acc[ai][bj][m][0] + x0, v1 = acc[ai][bj][m][1] + x1; acc[ai][bj][m][0] = v0; acc[ai][bj][m][1] = v1;
;                     ss += (v0[0] * v0[0] + v0[1] * v0[1]) + (v0[2] * v0[2] + v0[3] * v0[3]) + (v1[0] * v1[0] + v1[1] * v1[1]) + (v1[2] * v1[2] + v1[3] * v1[3]); }
;                 ss += __shfl_xor(ss, 16); ss += __shfl_xor(ss, 32);
;                 if (fq == 0) __hip_atomic_store(ssq + r * 16 + u.pn * 4 + wc, ss, __ATOMIC_RELAXED, __HIP_MEMORY_SCOPE_AGENT); }
.LBB0_430:
	v_lshl_add_u32 v176, s38, 8, v198
	v_lshl_or_b32 v178, s6, 8, v200
	v_ashrrev_i32_e32 v179, 31, v178
	v_ashrrev_i32_e32 v177, 31, v176
	v_lshl_add_u64 v[196:197], v[178:179], 1, s[16:17]
	v_lshlrev_b64 v[128:129], 11, v[176:177]
	v_lshl_add_u64 v[128:129], v[196:197], 0, v[128:129]
	global_load_dwordx4 v[180:183], v[128:129], off
	global_load_dwordx4 v[184:187], v[128:129], off offset:256
	v_or_b32_e32 v174, 16, v176
	v_or_b32_e32 v172, 32, v176
	v_or_b32_e32 v170, 48, v176
	v_ashrrev_i32_e32 v175, 31, v174
	v_ashrrev_i32_e32 v173, 31, v172
	v_ashrrev_i32_e32 v171, 31, v170
	v_lshlrev_b64 v[128:129], 11, v[174:175]
	v_lshlrev_b64 v[130:131], 11, v[172:173]
	v_lshlrev_b64 v[132:133], 11, v[170:171]
	v_lshl_add_u64 v[128:129], v[196:197], 0, v[128:129]
	v_lshl_add_u64 v[130:131], v[196:197], 0, v[130:131]
	v_lshl_add_u64 v[188:189], v[196:197], 0, v[132:133]
	global_load_dwordx4 v[148:151], v[128:129], off
	global_load_dwordx4 v[144:147], v[128:129], off offset:256
	global_load_dwordx4 v[140:143], v[130:131], off
	global_load_dwordx4 v[136:139], v[130:131], off offset:256
	global_load_dwordx4 v[132:135], v[188:189], off
	s_nop 0
	global_load_dwordx4 v[128:131], v[188:189], off offset:256
	v_lshlrev_b64 v[254:255], 11, v[176:177]
	v_lshl_add_u64 v[254:255], v[196:197], 0, v[254:255]
	s_mov_b64 s[60:61], 0x40000
	v_lshl_add_u64 v[254:255], v[254:255], 0, s[60:61]
	global_load_dwordx4 v[222:225], v[254:255], off
	global_load_dwordx4 v[226:229], v[254:255], off offset:256
	s_mov_b64 s[60:61], 0x8000
	v_lshl_add_u64 v[254:255], v[254:255], 0, s[60:61]
	global_load_dwordx4 v[230:233], v[254:255], off
	global_load_dwordx4 v[234:237], v[254:255], off offset:256
	v_lshl_add_u64 v[254:255], v[254:255], 0, s[60:61]
	global_load_dwordx4 v[238:241], v[254:255], off
	global_load_dwordx4 v[242:245], v[254:255], off offset:256
	v_lshl_add_u64 v[254:255], v[254:255], 0, s[60:61]
	global_load_dwordx4 v[246:249], v[254:255], off
	global_load_dwordx4 v[250:253], v[254:255], off offset:256
	v_and_b32_e32 v189, 64, v204
	v_xor_b32_e32 v188, 16, v204
	v_add_u32_e32 v207, 64, v189
	v_cmp_lt_i32_e32 vcc, v188, v207
	s_lshl_b32 s40, s6, 2
	s_ashr_i32 s41, s40, 31
	v_cndmask_b32_e32 v188, v204, v188, vcc
	v_lshlrev_b32_e32 v206, 2, v188
	s_waitcnt vmcnt(8)
	v_lshlrev_b32_e32 v188, 16, v180
	v_and_b32_e32 v189, 0xffff0000, v180
	v_lshlrev_b32_e32 v180, 16, v181
	v_and_b32_e32 v181, 0xffff0000, v181
	v_lshlrev_b32_e32 v192, 16, v184
	v_and_b32_e32 v193, 0xffff0000, v184
	v_lshlrev_b32_e32 v184, 16, v185
	v_and_b32_e32 v185, 0xffff0000, v185
	v_lshlrev_b32_e32 v190, 16, v182
	v_and_b32_e32 v191, 0xffff0000, v182
	v_lshlrev_b32_e32 v194, 16, v186
	v_and_b32_e32 v195, 0xffff0000, v186
	v_pk_add_f32 v[126:127], v[126:127], v[180:181]
	v_pk_add_f32 v[124:125], v[124:125], v[188:189]
	v_pk_add_f32 v[118:119], v[118:119], v[184:185]
	v_pk_add_f32 v[116:117], v[116:117], v[192:193]
	v_lshlrev_b32_e32 v182, 16, v183
	v_and_b32_e32 v183, 0xffff0000, v183
	v_lshlrev_b32_e32 v186, 16, v187
	v_and_b32_e32 v187, 0xffff0000, v187
	v_pk_add_f32 v[120:121], v[120:121], v[190:191]
	v_pk_add_f32 v[112:113], v[112:113], v[194:195]
	v_mul_f32_e32 v180, v125, v125
	v_mul_f32_e32 v181, v127, v127
	v_mul_f32_e32 v184, v117, v117
	v_mul_f32_e32 v185, v119, v119
	v_pk_add_f32 v[122:123], v[122:123], v[182:183]
	v_pk_add_f32 v[114:115], v[114:115], v[186:187]
	v_mul_f32_e32 v182, v121, v121
	v_mul_f32_e32 v186, v113, v113
	v_fmac_f32_e32 v180, v124, v124
	v_fmac_f32_e32 v181, v126, v126
	v_fmac_f32_e32 v184, v116, v116
	v_fmac_f32_e32 v185, v118, v118
	v_mul_f32_e32 v183, v123, v123
	v_mul_f32_e32 v187, v115, v115
	v_fmac_f32_e32 v182, v120, v120
	v_fmac_f32_e32 v186, v112, v112
	v_add_f32_e32 v180, v180, v181
	v_add_f32_e32 v181, v184, v185
	v_fmac_f32_e32 v183, v122, v122
	v_fmac_f32_e32 v187, v114, v114
	v_add_f32_e32 v180, v182, v180
	v_add_f32_e32 v181, v186, v181
	v_add_f32_e32 v180, v183, v180
	v_add_f32_e32 v181, v187, v181
	v_add_f32_e32 v180, v180, v181
	ds_bpermute_b32 v181, v206, v180
	v_xor_b32_e32 v182, 32, v204
	v_cmp_lt_i32_e32 vcc, v182, v207
	v_lshlrev_b64 v[188:189], 6, v[176:177]
	s_waitcnt lgkmcnt(0)
	v_add_f32_e32 v180, v180, v181
	v_cndmask_b32_e32 v182, v204, v182, vcc
	v_lshlrev_b32_e32 v207, 2, v182
	ds_bpermute_b32 v181, v207, v180
	s_and_saveexec_b64 s[42:43], s[0:1]
	s_cbranch_execz .LBB0_432
	s_waitcnt lgkmcnt(0)
	v_add_f32_e32 v182, v180, v181
	v_lshl_add_u64 v[180:181], s[10:11], 0, v[188:189]
	v_lshl_add_u64 v[180:181], s[40:41], 2, v[180:181]
	s_lshl_b32 s6, s53, 2
	v_lshl_add_u64 v[180:181], v[180:181], 0, s[6:7]
	global_store_dword v[180:181], v182, off sc1

;     __device__ __forceinline__ void operator()(f32x4 (&acc)[2][2][4][2], const Unit& u, int wr, int wc, int fr, int fq) const {
;     ...
;         for (int ai = 0; ai < 2; ++ai) {
;             u32x4 xv[4][2];
; #pragma unroll
;             for (int m = 0; m < 4; ++m)
; #pragma unroll
;                 for (int bj = 0; bj < 2; ++bj) { const size_t off = (size_t)(row0 + ai * HALF + m * 16) * DM + col0 + bj * HALF; xv[m][bj] = *(const u32x4*)(xb + off); }
; #pragma unroll
;             for (int m = 0; m < 4; ++m) { const size_t r = (size_t)(row0 + ai * HALF + m * 16); float ss = 0.f;
; #pragma unroll
;                 for (int bj = 0; bj < 2; ++bj) { const u32x4 xw = xv[m][bj];
;                     const f32x4 x0 = {bf_lo(xw.x), bf_hi(xw.x), bf_lo(xw.y), bf_hi(xw.y)}, x1 = {bf_lo(xw.z), bf_hi(xw.z), bf_lo(xw.w), bf_hi(xw.w)};
;                     const f32x4 v0 = acc[ai][bj][m][0] + x0, v1 = acc[ai][bj][m][1] + x1; acc[ai][bj][m][0] = v0; acc[ai][bj][m][1] = v1;
;                     ss += (v0[0] * v0[0] + v0[1] * v0[1]) + (v0[2] * v0[2] + v0[3] * v0[3]) + (v1[0] * v1[0] + v1[1] * v1[1]) + (v1[2] * v1[2] + v1[3] * v1[3]); }
;                 ss += __shfl_xor(ss, 16); ss += __shfl_xor(ss, 32);
;                 if (fq == 0) __hip_atomic_store(ssq + r * 16 + u.pn * 4 + wc, ss, __ATOMIC_RELAXED, __HIP_MEMORY_SCOPE_AGENT); }
.LBB0_438:
	s_or_b64 exec, exec, s[42:43]
	v_add_u32_e32 v186, 0x80, v176
	v_ashrrev_i32_e32 v187, 31, v186
	s_waitcnt lgkmcnt(0)
	v_lshlrev_b64 v[64:65], 11, v[186:187]
	v_lshl_add_u64 v[64:65], v[196:197], 0, v[64:65]
	s_waitcnt vmcnt(4)
	v_mov_b64_e32 v[208:209], v[222:223]
	v_mov_b64_e32 v[210:211], v[224:225]
	v_mov_b64_e32 v[212:213], v[226:227]
	v_mov_b64_e32 v[214:215], v[228:229]
	v_add_u32_e32 v92, 0x90, v176
	v_add_u32_e32 v90, 0xa0, v176
	v_add_u32_e32 v88, 0xb0, v176
	v_ashrrev_i32_e32 v93, 31, v92
	v_ashrrev_i32_e32 v91, 31, v90
	v_ashrrev_i32_e32 v89, 31, v88
	v_lshlrev_b64 v[64:65], 11, v[92:93]
	v_lshlrev_b64 v[66:67], 11, v[90:91]
	v_lshlrev_b64 v[68:69], 11, v[88:89]
	v_lshl_add_u64 v[64:65], v[196:197], 0, v[64:65]
	v_lshl_add_u64 v[66:67], v[196:197], 0, v[66:67]
	v_lshl_add_u64 v[196:197], v[196:197], 0, v[68:69]
	v_mov_b64_e32 v[84:85], v[230:231]
	v_mov_b64_e32 v[86:87], v[232:233]
	v_mov_b64_e32 v[80:81], v[234:235]
	v_mov_b64_e32 v[82:83], v[236:237]
	v_mov_b64_e32 v[76:77], v[238:239]
	v_mov_b64_e32 v[78:79], v[240:241]
	v_mov_b64_e32 v[72:73], v[242:243]
	v_mov_b64_e32 v[74:75], v[244:245]
	v_mov_b64_e32 v[68:69], v[246:247]
	v_mov_b64_e32 v[70:71], v[248:249]
	s_nop 0
	v_mov_b64_e32 v[64:65], v[250:251]
	v_mov_b64_e32 v[66:67], v[252:253]
	v_lshlrev_b32_e32 v196, 16, v208
	v_and_b32_e32 v197, 0xffff0000, v208
	v_lshlrev_b32_e32 v208, 16, v209
	v_and_b32_e32 v209, 0xffff0000, v209
	v_lshlrev_b32_e32 v218, 16, v212
	v_and_b32_e32 v219, 0xffff0000, v212
	v_lshlrev_b32_e32 v212, 16, v213
	v_and_b32_e32 v213, 0xffff0000, v213
	v_lshlrev_b32_e32 v216, 16, v210
	v_and_b32_e32 v217, 0xffff0000, v210
	v_lshlrev_b32_e32 v210, 16, v211
	v_and_b32_e32 v211, 0xffff0000, v211
	v_lshlrev_b32_e32 v220, 16, v214
	v_and_b32_e32 v221, 0xffff0000, v214
	v_pk_add_f32 v[62:63], v[62:63], v[208:209]
	v_pk_add_f32 v[60:61], v[60:61], v[196:197]
	v_pk_add_f32 v[54:55], v[54:55], v[212:213]
	v_pk_add_f32 v[52:53], v[52:53], v[218:219]
	v_lshlrev_b32_e32 v214, 16, v215
	v_and_b32_e32 v215, 0xffff0000, v215
	v_pk_add_f32 v[58:59], v[58:59], v[210:211]
	v_pk_add_f32 v[56:57], v[56:57], v[216:217]
	v_pk_add_f32 v[48:49], v[48:49], v[220:221]
	v_mul_f32_e32 v196, v61, v61
	v_mul_f32_e32 v197, v63, v63
	v_mul_f32_e32 v210, v53, v53
	v_mul_f32_e32 v211, v55, v55
	v_pk_add_f32 v[50:51], v[50:51], v[214:215]
	v_mul_f32_e32 v208, v57, v57
	v_mul_f32_e32 v212, v49, v49
	v_fmac_f32_e32 v196, v60, v60
	v_fmac_f32_e32 v197, v62, v62
	v_fmac_f32_e32 v210, v52, v52
	v_fmac_f32_e32 v211, v54, v54
	v_mul_f32_e32 v209, v59, v59
	v_mul_f32_e32 v213, v51, v51
	v_fmac_f32_e32 v208, v56, v56
	v_fmac_f32_e32 v212, v48, v48
	v_add_f32_e32 v196, v196, v197
	v_add_f32_e32 v197, v210, v211
	v_fmac_f32_e32 v209, v58, v58
	v_fmac_f32_e32 v213, v50, v50
	v_add_f32_e32 v196, v208, v196
	v_add_f32_e32 v197, v212, v197
	v_add_f32_e32 v196, v209, v196
	v_add_f32_e32 v197, v213, v197
	v_add_f32_e32 v196, v196, v197
	ds_bpermute_b32 v197, v206, v196
	s_waitcnt lgkmcnt(0)
	v_add_f32_e32 v208, v196, v197
	ds_bpermute_b32 v209, v207, v208
	v_lshlrev_b64 v[196:197], 6, v[186:187]
	s_and_saveexec_b64 s[42:43], s[0:1]
	s_cbranch_execz .LBB0_440
	s_waitcnt lgkmcnt(0)
	v_add_f32_e32 v210, v208, v209
	v_lshl_add_u64 v[208:209], s[10:11], 0, v[196:197]
	v_lshl_add_u64 v[208:209], s[40:41], 2, v[208:209]
	s_lshl_b32 s6, s53, 2
	v_lshl_add_u64 v[208:209], v[208:209], 0, s[6:7]
	global_store_dword v[208:209], v210, off sc1
.LBB0_440:
	s_or_b64 exec, exec, s[42:43]
	v_lshlrev_b32_e32 v208, 16, v84
	s_waitcnt lgkmcnt(0)
	v_and_b32_e32 v209, 0xffff0000, v84
	v_lshlrev_b32_e32 v84, 16, v85
	v_and_b32_e32 v85, 0xffff0000, v85
	v_pk_add_f32 v[46:47], v[46:47], v[84:85]
	v_pk_add_f32 v[44:45], v[44:45], v[208:209]
	v_lshlrev_b32_e32 v210, 16, v86
	v_and_b32_e32 v211, 0xffff0000, v86
	v_mul_f32_e32 v84, v45, v45
	v_mul_f32_e32 v85, v47, v47
	v_pk_add_f32 v[40:41], v[40:41], v[210:211]
	v_fmac_f32_e32 v84, v44, v44
	v_fmac_f32_e32 v85, v46, v46
	v_lshlrev_b32_e32 v86, 16, v87
	v_and_b32_e32 v87, 0xffff0000, v87
	v_add_f32_e32 v84, v84, v85
	v_mul_f32_e32 v85, v41, v41
	v_pk_add_f32 v[42:43], v[42:43], v[86:87]
	v_fmac_f32_e32 v85, v40, v40
	v_add_f32_e32 v84, v85, v84
	v_mul_f32_e32 v85, v43, v43
	v_fmac_f32_e32 v85, v42, v42
	v_add_f32_e32 v208, v85, v84
	v_lshlrev_b32_e32 v84, 16, v80
	v_and_b32_e32 v85, 0xffff0000, v80
	v_lshlrev_b32_e32 v80, 16, v81
	v_and_b32_e32 v81, 0xffff0000, v81
	v_lshlrev_b32_e32 v86, 16, v82
	v_and_b32_e32 v87, 0xffff0000, v82
	v_pk_add_f32 v[38:39], v[38:39], v[80:81]
	v_pk_add_f32 v[36:37], v[36:37], v[84:85]
	v_pk_add_f32 v[80:81], v[32:33], v[86:87]
	v_mul_f32_e32 v32, v37, v37
	v_mul_f32_e32 v33, v39, v39
	v_fmac_f32_e32 v32, v36, v36
	v_fmac_f32_e32 v33, v38, v38
	v_lshlrev_b32_e32 v82, 16, v83
	v_and_b32_e32 v83, 0xffff0000, v83
	v_add_f32_e32 v32, v32, v33
	v_mul_f32_e32 v33, v81, v81
	v_pk_add_f32 v[34:35], v[34:35], v[82:83]
	v_fmac_f32_e32 v33, v80, v80
	v_add_f32_e32 v32, v33, v32
	v_mul_f32_e32 v33, v35, v35
	v_fmac_f32_e32 v33, v34, v34
	v_add_f32_e32 v32, v33, v32
	v_add_f32_e32 v32, v208, v32
	ds_bpermute_b32 v33, v206, v32
	v_lshlrev_b64 v[82:83], 6, v[92:93]
	s_waitcnt lgkmcnt(0)
	v_add_f32_e32 v32, v32, v33
	ds_bpermute_b32 v33, v207, v32
	s_and_saveexec_b64 s[42:43], s[0:1]
	s_cbranch_execz .LBB0_442
	s_waitcnt lgkmcnt(0)
	v_add_f32_e32 v84, v32, v33
	v_lshl_add_u64 v[32:33], s[10:11], 0, v[82:83]
	v_lshl_add_u64 v[32:33], s[40:41], 2, v[32:33]
	s_lshl_b32 s6, s53, 2
	v_lshl_add_u64 v[32:33], v[32:33], 0, s[6:7]
	global_store_dword v[32:33], v84, off sc1
;     __device__ __forceinline__ void operator()(f32x4 (&acc)[2][2][4][2], const Unit& u, int wr, int wc, int fr, int fq) const {
;     ...
;             for (int m = 0; m < 4; ++m) { const size_t r = (size_t)(row0 + ai * HALF + m * 16); float ss = 0.f;
; #pragma unroll
;                 for (int bj = 0; bj < 2; ++bj) { const u32x4 xw = xv[m][bj];
;                     const f32x4 x0 = {bf_lo(xw.x), bf_hi(xw.x), bf_lo(xw.y), bf_hi(xw.y)}, x1 = {bf_lo(xw.z), bf_hi(xw.z), bf_lo(xw.w), bf_hi(xw.w)};
;                     const f32x4 v0 = acc[ai][bj][m][0] + x0, v1 = acc[ai][bj][m][1] + x1; acc[ai][bj][m][0] = v0; acc[ai][bj][m][1] = v1;
;                     ss += (v0[0] * v0[0] + v0[1] * v0[1]) + (v0[2] * v0[2] + v0[3] * v0[3]) + (v1[0] * v1[0] + v1[1] * v1[1]) + (v1[2] * v1[2] + v1[3] * v1[3]); }
;                 ss += __shfl_xor(ss, 16); ss += __shfl_xor(ss, 32);
;                 if (fq == 0) __hip_atomic_store(ssq + r * 16 + u.pn * 4 + wc, ss, __ATOMIC_RELAXED, __HIP_MEMORY_SCOPE_AGENT); }
;             asm volatile("" ::: "memory"); }
;         asm volatile("s_waitcnt vmcnt(0)" ::: "memory");
;         unsigned* pc = cnt + 64 * u.pm;
;         if (fr == 0 && fq == 0) __hip_atomic_fetch_add(pc, 1u, __ATOMIC_RELAXED, __HIP_MEMORY_SCOPE_AGENT);
.LBB0_442:
	s_or_b64 exec, exec, s[42:43]
	v_lshlrev_b32_e32 v32, 16, v76
	s_waitcnt lgkmcnt(0)
	v_and_b32_e32 v33, 0xffff0000, v76
	v_lshlrev_b32_e32 v76, 16, v77
	v_and_b32_e32 v77, 0xffff0000, v77
	v_pk_add_f32 v[30:31], v[30:31], v[76:77]
	v_pk_add_f32 v[28:29], v[28:29], v[32:33]
	v_lshlrev_b32_e32 v84, 16, v78
	v_and_b32_e32 v85, 0xffff0000, v78
	v_mul_f32_e32 v32, v29, v29
	v_mul_f32_e32 v33, v31, v31
	v_pk_add_f32 v[24:25], v[24:25], v[84:85]
	v_fmac_f32_e32 v32, v28, v28
	v_fmac_f32_e32 v33, v30, v30
	v_lshlrev_b32_e32 v78, 16, v79
	v_and_b32_e32 v79, 0xffff0000, v79
	v_add_f32_e32 v32, v32, v33
	v_mul_f32_e32 v33, v25, v25
	v_pk_add_f32 v[26:27], v[26:27], v[78:79]
	v_fmac_f32_e32 v33, v24, v24
	v_add_f32_e32 v32, v33, v32
	v_mul_f32_e32 v33, v27, v27
	v_fmac_f32_e32 v33, v26, v26
	v_add_f32_e32 v84, v33, v32
	v_lshlrev_b32_e32 v76, 16, v72
	v_and_b32_e32 v77, 0xffff0000, v72
	v_lshlrev_b32_e32 v32, 16, v73
	v_and_b32_e32 v33, 0xffff0000, v73
	v_lshlrev_b32_e32 v78, 16, v74
	v_and_b32_e32 v79, 0xffff0000, v74
	v_pk_add_f32 v[32:33], v[22:23], v[32:33]
	v_pk_add_f32 v[72:73], v[20:21], v[76:77]
	v_pk_add_f32 v[76:77], v[16:17], v[78:79]
	v_mul_f32_e32 v16, v73, v73
	v_mul_f32_e32 v17, v33, v33
	v_fmac_f32_e32 v16, v72, v72
	v_fmac_f32_e32 v17, v32, v32
	v_lshlrev_b32_e32 v74, 16, v75
	v_and_b32_e32 v75, 0xffff0000, v75
	v_add_f32_e32 v16, v16, v17
	v_mul_f32_e32 v17, v77, v77
	v_pk_add_f32 v[74:75], v[18:19], v[74:75]
	v_fmac_f32_e32 v17, v76, v76
	v_add_f32_e32 v16, v17, v16
	v_mul_f32_e32 v17, v75, v75
	v_fmac_f32_e32 v17, v74, v74
	v_add_f32_e32 v16, v17, v16
	v_add_f32_e32 v16, v84, v16
	ds_bpermute_b32 v17, v206, v16
	v_lshlrev_b64 v[78:79], 6, v[90:91]
	s_waitcnt lgkmcnt(0)
	v_add_f32_e32 v16, v16, v17
	ds_bpermute_b32 v17, v207, v16
	s_and_saveexec_b64 s[42:43], s[0:1]
	s_cbranch_execz .LBB0_444
	s_waitcnt lgkmcnt(0)
	v_add_f32_e32 v18, v16, v17
	v_lshl_add_u64 v[16:17], s[10:11], 0, v[78:79]
	v_lshl_add_u64 v[16:17], s[40:41], 2, v[16:17]
	s_lshl_b32 s6, s53, 2
	v_lshl_add_u64 v[16:17], v[16:17], 0, s[6:7]
	global_store_dword v[16:17], v18, off sc1
.LBB0_444:
	s_or_b64 exec, exec, s[42:43]
	v_lshlrev_b32_e32 v18, 16, v68
	v_and_b32_e32 v19, 0xffff0000, v68
	v_lshlrev_b32_e32 v16, 16, v69
	s_waitcnt lgkmcnt(0)
	v_and_b32_e32 v17, 0xffff0000, v69
	v_lshlrev_b32_e32 v22, 16, v70
	v_and_b32_e32 v23, 0xffff0000, v70
	v_pk_add_f32 v[16:17], v[14:15], v[16:17]
	v_pk_add_f32 v[18:19], v[12:13], v[18:19]
	v_pk_add_f32 v[22:23], v[8:9], v[22:23]
	v_mul_f32_e32 v8, v19, v19
	v_mul_f32_e32 v9, v17, v17
	v_fmac_f32_e32 v8, v18, v18
	v_fmac_f32_e32 v9, v16, v16
	v_lshlrev_b32_e32 v20, 16, v71
	v_and_b32_e32 v21, 0xffff0000, v71
	v_add_f32_e32 v8, v8, v9
	v_mul_f32_e32 v9, v23, v23
	v_pk_add_f32 v[20:21], v[10:11], v[20:21]
	v_fmac_f32_e32 v9, v22, v22
	v_add_f32_e32 v8, v9, v8
	v_mul_f32_e32 v9, v21, v21
	v_fmac_f32_e32 v9, v20, v20
	v_add_f32_e32 v84, v9, v8
	v_lshlrev_b32_e32 v8, 16, v64
	v_and_b32_e32 v9, 0xffff0000, v64
	v_lshlrev_b32_e32 v10, 16, v65
	v_and_b32_e32 v11, 0xffff0000, v65
	v_lshlrev_b32_e32 v12, 16, v66
	v_and_b32_e32 v13, 0xffff0000, v66
	v_lshlrev_b32_e32 v14, 16, v67
	v_and_b32_e32 v15, 0xffff0000, v67
	v_pk_add_f32 v[64:65], v[6:7], v[10:11]
	v_pk_add_f32 v[66:67], v[4:5], v[8:9]
	v_pk_add_f32 v[70:71], v[0:1], v[12:13]
	v_mul_f32_e32 v0, v67, v67
	v_mul_f32_e32 v1, v65, v65
	v_fmac_f32_e32 v0, v66, v66
	v_fmac_f32_e32 v1, v64, v64
	v_add_f32_e32 v0, v0, v1
	v_mul_f32_e32 v1, v71, v71
	v_pk_add_f32 v[68:69], v[2:3], v[14:15]
	v_fmac_f32_e32 v1, v70, v70
	v_add_f32_e32 v0, v1, v0
	v_mul_f32_e32 v1, v69, v69
	v_fmac_f32_e32 v1, v68, v68
	v_add_f32_e32 v0, v1, v0
	v_add_f32_e32 v0, v84, v0
	ds_bpermute_b32 v1, v206, v0
	v_lshlrev_b64 v[84:85], 6, v[88:89]
	s_waitcnt lgkmcnt(0)
	v_add_f32_e32 v0, v0, v1
	ds_bpermute_b32 v1, v207, v0
	s_and_saveexec_b64 s[42:43], s[0:1]
	s_cbranch_execz .LBB0_446
	s_waitcnt lgkmcnt(0)
	v_add_f32_e32 v2, v0, v1
	v_lshl_add_u64 v[0:1], s[10:11], 0, v[84:85]
	v_lshl_add_u64 v[0:1], s[40:41], 2, v[0:1]
	s_lshl_b32 s6, s53, 2
	v_lshl_add_u64 v[0:1], v[0:1], 0, s[6:7]
	global_store_dword v[0:1], v2, off sc1
.LBB0_446:
	s_or_b64 exec, exec, s[42:43]
	s_lshl_b32 s38, s38, 6
	s_waitcnt vmcnt(0)
	s_ashr_i32 s39, s38, 31
	s_lshl_b64 s[38:39], s[38:39], 2
	s_add_u32 s38, s51, s38
	s_addc_u32 s39, s52, s39
	s_and_saveexec_b64 s[40:41], s[2:3]
	s_cbranch_execz .LBB0_449
	s_mov_b64 s[42:43], exec
	v_mbcnt_lo_u32_b32 v0, s42, 0
	v_mbcnt_hi_u32_b32 v0, s43, v0
	v_cmp_eq_u32_e32 vcc, 0, v0
	s_and_b64 s[44:45], exec, vcc
	s_mov_b64 exec, s[44:45]
	s_cbranch_execz .LBB0_449
	s_bcnt1_i32_b64 s6, s[42:43]
	v_mov_b32_e32 v0, s6
	global_atomic_add v155, v0, s[38:39]
